# attention QK^T inner loop: replaced lgkmcnt(0) drains every 3 k-steps by exact counted lgkmcnt waits per MFMA
# baseline (speedup 1.0000x reference)
; #define SBAR() __builtin_amdgcn_sched_barrier(0)
; #define KLD(d) do { k0[(d) % 4] = *reinterpret_cast<const bf16x8*>(kb + (d) * 512); k1[(d) % 4] = *reinterpret_cast<const bf16x8*>(kb + 12288 + (d) * 512); } while (0)
; #define KLD(d) do { k0[(d) % 4] = *reinterpret_cast<const bf16x8*>(kb + (d) * 512); k1[(d) % 4] = *reinterpret_cast<const bf16x8*>(kb + 12288 + (d) * 512); } while (0)
; __device__ __forceinline__ void qkt_pv(f32x16& p0, f32x16& p1, const char* Ks, const bf16x8* qr, const char* Qr, int kbase, f32x16* o, int vb, bf16x8 pa0, bf16x8 pa1, bf16x8 pa2, bf16x8 pa3) {
;   p0 = f32x16{}; p1 = f32x16{};
;   const char* kb = Ks + kbase;
;   bf16x8 k0[4], k1[4]; VFrag fa, fb;
;     ...
;   KLD(0); KLD(1); KLD(2);
;   __builtin_amdgcn_s_setprio(1);
; #pragma unroll
;   for (int d0 = 0; d0 < 12; ++d0) {
;     if (d0 + 3 < 12) KLD(d0 + 3);
;     if (d0 == 10) v_read8<0>(fa, vb);
;     const bf16x8 qf = d0 < NQREG ? qr[d0 < NQREG ? d0 : 0] : *reinterpret_cast<const bf16x8*>(Qr + (d0 - NQREG) * 8192);
;     p0 = __builtin_amdgcn_mfma_f32_32x32x16_bf16(k0[d0 % 4], qf, p0, 0, 0, 0);
;     p1 = __builtin_amdgcn_mfma_f32_32x32x16_bf16(k1[d0 % 4], qf, p1, 0, 0, 0);
;     SBAR(); }
;     ...
;   v_read8<1>(fb, vb);
;   asm volatile("s_waitcnt lgkmcnt(8)" ::: "memory"); SBAR(); pv_mma(o[0], fa, pa0, pa1, pa2, pa3); SBAR();
;   v_read8<2>(fa, vb);
;   asm volatile("s_waitcnt lgkmcnt(8)" ::: "memory"); SBAR(); pv_mma(o[1], fb, pa0, pa1, pa2, pa3); SBAR();
;   v_read8<3>(fb, vb);
;   asm volatile("s_waitcnt lgkmcnt(8)" ::: "memory"); SBAR(); pv_mma(o[2], fa, pa0, pa1, pa2, pa3); SBAR();
;   asm volatile("s_waitcnt lgkmcnt(0)" ::: "memory"); SBAR(); pv_mma(o[3], fb, pa0, pa1, pa2, pa3); SBAR();
;   __builtin_amdgcn_s_setprio(0);
; }
.LBB0_1113:
	s_mov_b32 s6, s40
	s_mov_b32 s40, s72
	s_mul_i32 s7, s72, 0x6000
	v_add_u32_e32 v46, s7, v211
	ds_read_b128 v[80:83], v46
	ds_read_b128 v[214:217], v46 offset:512
	ds_read_b128 v[84:87], v46 offset:12288
	ds_read_b128 v[218:221], v46 offset:1024
	ds_read_b128 v[222:225], v46 offset:12800
	ds_read_b128 v[226:229], v46 offset:13312
	v_lshl_add_u32 v187, s6, 14, v209
	s_setprio 1
	s_waitcnt lgkmcnt(5)
	v_mfma_f32_32x32x16_bf16 v[96:111], v[80:83], v[112:115], 0
	ds_read_b128 v[230:233], v46 offset:1536
	ds_read_b128 v[234:237], v46 offset:13824
	s_waitcnt lgkmcnt(5)
	v_mfma_f32_32x32x16_bf16 v[80:95], v[84:87], v[112:115], 0
	v_mfma_f32_32x32x16_bf16 v[96:111], v[214:217], v[116:119], v[96:111]
	ds_read_b128 v[214:217], v46 offset:2048
	ds_read_b128 v[238:241], v46 offset:14336
	s_waitcnt lgkmcnt(5)
	v_mfma_f32_32x32x16_bf16 v[80:95], v[222:225], v[116:119], v[80:95]
	v_mfma_f32_32x32x16_bf16 v[96:111], v[218:221], v[120:123], v[96:111]
	ds_read_b128 v[218:221], v46 offset:2560
	ds_read_b128 v[222:225], v46 offset:14848
	s_waitcnt lgkmcnt(6)
	v_mfma_f32_32x32x16_bf16 v[80:95], v[226:229], v[120:123], v[80:95]
	s_waitcnt lgkmcnt(5)
	v_mfma_f32_32x32x16_bf16 v[96:111], v[230:233], v[124:127], v[96:111]
	ds_read_b128 v[226:229], v46 offset:3072
	ds_read_b128 v[230:233], v46 offset:15360
	s_waitcnt lgkmcnt(6)
	v_mfma_f32_32x32x16_bf16 v[80:95], v[234:237], v[124:127], v[80:95]
	s_waitcnt lgkmcnt(5)
	v_mfma_f32_32x32x16_bf16 v[96:111], v[214:217], v[128:131], v[96:111]
	ds_read_b128 v[214:217], v46 offset:3584
	ds_read_b128 v[234:237], v46 offset:15872
	s_waitcnt lgkmcnt(6)
	v_mfma_f32_32x32x16_bf16 v[80:95], v[238:241], v[128:131], v[80:95]
	s_waitcnt lgkmcnt(5)
	v_mfma_f32_32x32x16_bf16 v[96:111], v[218:221], v[132:135], v[96:111]
	ds_read_b128 v[218:221], v46 offset:4096
	ds_read_b128 v[238:241], v46 offset:16384
	s_waitcnt lgkmcnt(6)
	v_mfma_f32_32x32x16_bf16 v[80:95], v[222:225], v[132:135], v[80:95]
	s_waitcnt lgkmcnt(5)
	v_mfma_f32_32x32x16_bf16 v[96:111], v[226:229], v[136:139], v[96:111]
	ds_read_b128 v[222:225], v46 offset:4608
	ds_read_b128 v[226:229], v46 offset:16896
	s_waitcnt lgkmcnt(6)
	v_mfma_f32_32x32x16_bf16 v[80:95], v[230:233], v[136:139], v[80:95]
	s_waitcnt lgkmcnt(5)
	v_mfma_f32_32x32x16_bf16 v[96:111], v[214:217], v[140:143], v[96:111]
	ds_read_b128 v[214:217], v46 offset:5120
	ds_read_b128 v[230:233], v46 offset:17408
	s_waitcnt lgkmcnt(6)
	v_mfma_f32_32x32x16_bf16 v[80:95], v[234:237], v[140:143], v[80:95]
	s_waitcnt lgkmcnt(5)
	v_mfma_f32_32x32x16_bf16 v[96:111], v[218:221], v[144:147], v[96:111]
	ds_read_b128 v[218:221], v46 offset:5632
	ds_read_b128 v[234:237], v46 offset:17920
	s_waitcnt lgkmcnt(6)
	v_mfma_f32_32x32x16_bf16 v[80:95], v[238:241], v[144:147], v[80:95]
	s_waitcnt lgkmcnt(5)
	v_mfma_f32_32x32x16_bf16 v[96:111], v[222:225], v[148:151], v[96:111]
	s_waitcnt lgkmcnt(4)
	v_mfma_f32_32x32x16_bf16 v[80:95], v[226:229], v[148:151], v[80:95]
	ds_read_b64_tr_b16 v[222:223], v187 offset:0
	ds_read_b64_tr_b16 v[224:225], v187 offset:0x800
	s_waitcnt lgkmcnt(5)
	v_mfma_f32_32x32x16_bf16 v[96:111], v[214:217], v[152:155], v[96:111]
	ds_read_b64_tr_b16 v[214:215], v187 offset:0x1000
	ds_read_b64_tr_b16 v[216:217], v187 offset:0x1800
	ds_read_b64_tr_b16 v[226:227], v187 offset:0x2000
	ds_read_b64_tr_b16 v[228:229], v187 offset:0x2800
	ds_read_b64_tr_b16 v[238:239], v187 offset:0x3000
	ds_read_b64_tr_b16 v[240:241], v187 offset:0x3800
	s_waitcnt lgkmcnt(10)
	v_mfma_f32_32x32x16_bf16 v[80:95], v[230:233], v[152:155], v[80:95]
	s_waitcnt lgkmcnt(9)
	v_mfma_f32_32x32x16_bf16 v[96:111], v[218:221], v[156:159], v[96:111]
	s_waitcnt lgkmcnt(8)
	v_mfma_f32_32x32x16_bf16 v[80:95], v[234:237], v[156:159], v[80:95]
	ds_read_b64_tr_b16 v[218:219], v187 offset:0x200
	ds_read_b64_tr_b16 v[220:221], v187 offset:0xa00
	ds_read_b64_tr_b16 v[230:231], v187 offset:0x1200
	ds_read_b64_tr_b16 v[232:233], v187 offset:0x1a00
	ds_read_b64_tr_b16 v[234:235], v187 offset:0x2200
	ds_read_b64_tr_b16 v[236:237], v187 offset:0x2a00
	ds_read_b64_tr_b16 v[242:243], v187 offset:0x3200
	ds_read_b64_tr_b16 v[244:245], v187 offset:0x3a00
	s_waitcnt lgkmcnt(8)
	v_mfma_f32_32x32x16_bf16 v[64:79], v[34:37], v[222:225], v[64:79]
	v_mfma_f32_32x32x16_bf16 v[64:79], v[38:41], v[214:217], v[64:79]
	v_mfma_f32_32x32x16_bf16 v[64:79], v[42:45], v[226:229], v[64:79]
	v_mfma_f32_32x32x16_bf16 v[64:79], v[160:163], v[238:241], v[64:79]
	ds_read_b64_tr_b16 v[214:215], v187 offset:0x400
	ds_read_b64_tr_b16 v[216:217], v187 offset:0xc00
	ds_read_b64_tr_b16 v[222:223], v187 offset:0x1400
	ds_read_b64_tr_b16 v[224:225], v187 offset:0x1c00
	ds_read_b64_tr_b16 v[226:227], v187 offset:0x2400
	ds_read_b64_tr_b16 v[228:229], v187 offset:0x2c00
	ds_read_b64_tr_b16 v[238:239], v187 offset:0x3400
	ds_read_b64_tr_b16 v[240:241], v187 offset:0x3c00
	s_waitcnt lgkmcnt(8)
	v_mfma_f32_32x32x16_bf16 v[48:63], v[34:37], v[218:221], v[48:63]
	v_mfma_f32_32x32x16_bf16 v[48:63], v[38:41], v[230:233], v[48:63]
	v_mfma_f32_32x32x16_bf16 v[48:63], v[42:45], v[234:237], v[48:63]
	v_mfma_f32_32x32x16_bf16 v[48:63], v[160:163], v[242:245], v[48:63]
	ds_read_b64_tr_b16 v[218:219], v187 offset:0x600
	ds_read_b64_tr_b16 v[220:221], v187 offset:0xe00
	ds_read_b64_tr_b16 v[230:231], v187 offset:0x1600
	ds_read_b64_tr_b16 v[232:233], v187 offset:0x1e00
	ds_read_b64_tr_b16 v[234:235], v187 offset:0x2600
	ds_read_b64_tr_b16 v[236:237], v187 offset:0x2e00
	ds_read_b64_tr_b16 v[242:243], v187 offset:0x3600
	ds_read_b64_tr_b16 v[244:245], v187 offset:0x3e00
	s_waitcnt lgkmcnt(8)
	v_mfma_f32_32x32x16_bf16 v[16:31], v[34:37], v[214:217], v[16:31]
	v_mfma_f32_32x32x16_bf16 v[16:31], v[38:41], v[222:225], v[16:31]
	v_mfma_f32_32x32x16_bf16 v[16:31], v[42:45], v[226:229], v[16:31]
	v_mfma_f32_32x32x16_bf16 v[16:31], v[160:163], v[238:241], v[16:31]
	s_waitcnt lgkmcnt(0)
	v_mfma_f32_32x32x16_bf16 v[0:15], v[34:37], v[218:221], v[0:15]
	v_mfma_f32_32x32x16_bf16 v[0:15], v[38:41], v[230:233], v[0:15]
	v_mfma_f32_32x32x16_bf16 v[0:15], v[42:45], v[234:237], v[0:15]
	v_mfma_f32_32x32x16_bf16 v[0:15], v[160:163], v[242:245], v[0:15]
	s_setprio 0
	s_and_b64 vcc, exec, s[8:9]
	s_cbranch_vccnz .LBB0_1115
	s_waitcnt vmcnt(0)

; #define SBAR() __builtin_amdgcn_sched_barrier(0)
; #define KLD(d) do { k0[(d) % 4] = *reinterpret_cast<const bf16x8*>(kb + (d) * 512); k1[(d) % 4] = *reinterpret_cast<const bf16x8*>(kb + 12288 + (d) * 512); } while (0)
; #define KLD(d) do { k0[(d) % 4] = *reinterpret_cast<const bf16x8*>(kb + (d) * 512); k1[(d) % 4] = *reinterpret_cast<const bf16x8*>(kb + 12288 + (d) * 512); } while (0)
; __device__ __forceinline__ void qkt_pv(f32x16& p0, f32x16& p1, const char* Ks, const bf16x8* qr, const char* Qr, int kbase, f32x16* o, int vb, bf16x8 pa0, bf16x8 pa1, bf16x8 pa2, bf16x8 pa3) {
;   p0 = f32x16{}; p1 = f32x16{};
;   const char* kb = Ks + kbase;
;   bf16x8 k0[4], k1[4]; VFrag fa, fb;
;     ...
;   KLD(0); KLD(1); KLD(2);
;   __builtin_amdgcn_s_setprio(1);
; #pragma unroll
;   for (int d0 = 0; d0 < 12; ++d0) {
;     if (d0 + 3 < 12) KLD(d0 + 3);
;     if (d0 == 10) v_read8<0>(fa, vb);
;     const bf16x8 qf = d0 < NQREG ? qr[d0 < NQREG ? d0 : 0] : *reinterpret_cast<const bf16x8*>(Qr + (d0 - NQREG) * 8192);
;     p0 = __builtin_amdgcn_mfma_f32_32x32x16_bf16(k0[d0 % 4], qf, p0, 0, 0, 0);
;     p1 = __builtin_amdgcn_mfma_f32_32x32x16_bf16(k1[d0 % 4], qf, p1, 0, 0, 0);
;     SBAR(); }
;     ...
;   v_read8<1>(fb, vb);
;   asm volatile("s_waitcnt lgkmcnt(8)" ::: "memory"); SBAR(); pv_mma(o[0], fa, pa0, pa1, pa2, pa3); SBAR();
;   v_read8<2>(fa, vb);
;   asm volatile("s_waitcnt lgkmcnt(8)" ::: "memory"); SBAR(); pv_mma(o[1], fb, pa0, pa1, pa2, pa3); SBAR();
;   v_read8<3>(fb, vb);
;   asm volatile("s_waitcnt lgkmcnt(8)" ::: "memory"); SBAR(); pv_mma(o[2], fa, pa0, pa1, pa2, pa3); SBAR();
;   asm volatile("s_waitcnt lgkmcnt(0)" ::: "memory"); SBAR(); pv_mma(o[3], fb, pa0, pa1, pa2, pa3); SBAR();
;   __builtin_amdgcn_s_setprio(0);
; }
; __device__ __forceinline__ void attn_phase(const bf16_t* __restrict__ Q, const bf16_t* __restrict__ KN, const bf16_t* __restrict__ KR, const bf16_t* __restrict__ V, ...
;     ...
;         const bool qpre_ = (j == NT - 1 && ui + 1 < nun_wg);
;         if (qpre_) LOADQ(vcu + (ui + 1) * G);
.LBB0_1133:
	s_add_i32 s70, s70, 1
	s_cmp_ge_i32 s70, s47
	s_cselect_b64 s[6:7], -1, 0
	s_mul_i32 s30, s72, 0x6000
	v_add_u32_e32 v47, s30, v211
	ds_read_b128 v[80:83], v47
	ds_read_b128 v[214:217], v47 offset:512
	ds_read_b128 v[84:87], v47 offset:12288
	ds_read_b128 v[218:221], v47 offset:1024
	ds_read_b128 v[222:225], v47 offset:12800
	ds_read_b128 v[226:229], v47 offset:13312
	v_lshl_add_u32 v187, s40, 14, v209
	s_setprio 1
	s_waitcnt lgkmcnt(5)
	v_mfma_f32_32x32x16_bf16 v[96:111], v[80:83], v[112:115], 0
	ds_read_b128 v[230:233], v47 offset:1536
	ds_read_b128 v[234:237], v47 offset:13824
	s_waitcnt lgkmcnt(5)
	v_mfma_f32_32x32x16_bf16 v[80:95], v[84:87], v[112:115], 0
	v_mfma_f32_32x32x16_bf16 v[96:111], v[214:217], v[116:119], v[96:111]
	ds_read_b128 v[214:217], v47 offset:2048
	ds_read_b128 v[238:241], v47 offset:14336
	s_waitcnt lgkmcnt(5)
	v_mfma_f32_32x32x16_bf16 v[80:95], v[222:225], v[116:119], v[80:95]
	v_mfma_f32_32x32x16_bf16 v[96:111], v[218:221], v[120:123], v[96:111]
	ds_read_b128 v[218:221], v47 offset:2560
	ds_read_b128 v[222:225], v47 offset:14848
	s_waitcnt lgkmcnt(6)
	v_mfma_f32_32x32x16_bf16 v[80:95], v[226:229], v[120:123], v[80:95]
	s_waitcnt lgkmcnt(5)
	v_mfma_f32_32x32x16_bf16 v[96:111], v[230:233], v[124:127], v[96:111]
	ds_read_b128 v[226:229], v47 offset:3072
	ds_read_b128 v[230:233], v47 offset:15360
	s_waitcnt lgkmcnt(6)
	v_mfma_f32_32x32x16_bf16 v[80:95], v[234:237], v[124:127], v[80:95]
	s_waitcnt lgkmcnt(5)
	v_mfma_f32_32x32x16_bf16 v[96:111], v[214:217], v[128:131], v[96:111]
	ds_read_b128 v[214:217], v47 offset:3584
	ds_read_b128 v[234:237], v47 offset:15872
	s_waitcnt lgkmcnt(6)
	v_mfma_f32_32x32x16_bf16 v[80:95], v[238:241], v[128:131], v[80:95]
	s_waitcnt lgkmcnt(5)
	v_mfma_f32_32x32x16_bf16 v[96:111], v[218:221], v[132:135], v[96:111]
	ds_read_b128 v[218:221], v47 offset:4096
	ds_read_b128 v[238:241], v47 offset:16384
	s_waitcnt lgkmcnt(6)
	v_mfma_f32_32x32x16_bf16 v[80:95], v[222:225], v[132:135], v[80:95]
	s_waitcnt lgkmcnt(5)
	v_mfma_f32_32x32x16_bf16 v[96:111], v[226:229], v[136:139], v[96:111]
	ds_read_b128 v[222:225], v47 offset:4608
	ds_read_b128 v[226:229], v47 offset:16896
	s_waitcnt lgkmcnt(6)
	v_mfma_f32_32x32x16_bf16 v[80:95], v[230:233], v[136:139], v[80:95]
	s_waitcnt lgkmcnt(5)
	v_mfma_f32_32x32x16_bf16 v[96:111], v[214:217], v[140:143], v[96:111]
	ds_read_b128 v[214:217], v47 offset:5120
	ds_read_b128 v[230:233], v47 offset:17408
	s_waitcnt lgkmcnt(6)
	v_mfma_f32_32x32x16_bf16 v[80:95], v[234:237], v[140:143], v[80:95]
	s_waitcnt lgkmcnt(5)
	v_mfma_f32_32x32x16_bf16 v[96:111], v[218:221], v[144:147], v[96:111]
	ds_read_b128 v[218:221], v47 offset:5632
	ds_read_b128 v[234:237], v47 offset:17920
	s_waitcnt lgkmcnt(6)
	v_mfma_f32_32x32x16_bf16 v[80:95], v[238:241], v[144:147], v[80:95]
	s_waitcnt lgkmcnt(5)
	v_mfma_f32_32x32x16_bf16 v[96:111], v[222:225], v[148:151], v[96:111]
	s_waitcnt lgkmcnt(4)
	v_mfma_f32_32x32x16_bf16 v[80:95], v[226:229], v[148:151], v[80:95]
	ds_read_b64_tr_b16 v[222:223], v187 offset:0
	ds_read_b64_tr_b16 v[224:225], v187 offset:0x800
	s_waitcnt lgkmcnt(5)
	v_mfma_f32_32x32x16_bf16 v[96:111], v[214:217], v[152:155], v[96:111]
	ds_read_b64_tr_b16 v[214:215], v187 offset:0x1000
	ds_read_b64_tr_b16 v[216:217], v187 offset:0x1800
	ds_read_b64_tr_b16 v[226:227], v187 offset:0x2000
	ds_read_b64_tr_b16 v[228:229], v187 offset:0x2800
	ds_read_b64_tr_b16 v[238:239], v187 offset:0x3000
	ds_read_b64_tr_b16 v[240:241], v187 offset:0x3800
	s_waitcnt lgkmcnt(10)
	v_mfma_f32_32x32x16_bf16 v[80:95], v[230:233], v[152:155], v[80:95]
	s_waitcnt lgkmcnt(9)
	v_mfma_f32_32x32x16_bf16 v[96:111], v[218:221], v[156:159], v[96:111]
	s_waitcnt lgkmcnt(8)
	v_mfma_f32_32x32x16_bf16 v[80:95], v[234:237], v[156:159], v[80:95]
	ds_read_b64_tr_b16 v[218:219], v187 offset:0x200
	ds_read_b64_tr_b16 v[220:221], v187 offset:0xa00
	ds_read_b64_tr_b16 v[230:231], v187 offset:0x1200
	ds_read_b64_tr_b16 v[232:233], v187 offset:0x1a00
	ds_read_b64_tr_b16 v[234:235], v187 offset:0x2200
	ds_read_b64_tr_b16 v[236:237], v187 offset:0x2a00
	ds_read_b64_tr_b16 v[242:243], v187 offset:0x3200
	ds_read_b64_tr_b16 v[244:245], v187 offset:0x3a00
	s_waitcnt lgkmcnt(8)
	v_mfma_f32_32x32x16_bf16 v[64:79], v[34:37], v[222:225], v[64:79]
	v_mfma_f32_32x32x16_bf16 v[64:79], v[38:41], v[214:217], v[64:79]
	v_mfma_f32_32x32x16_bf16 v[64:79], v[42:45], v[226:229], v[64:79]
	v_mfma_f32_32x32x16_bf16 v[64:79], v[160:163], v[238:241], v[64:79]
	ds_read_b64_tr_b16 v[214:215], v187 offset:0x400
	ds_read_b64_tr_b16 v[216:217], v187 offset:0xc00
	ds_read_b64_tr_b16 v[222:223], v187 offset:0x1400
	ds_read_b64_tr_b16 v[224:225], v187 offset:0x1c00
	ds_read_b64_tr_b16 v[226:227], v187 offset:0x2400
	ds_read_b64_tr_b16 v[228:229], v187 offset:0x2c00
	ds_read_b64_tr_b16 v[238:239], v187 offset:0x3400
	ds_read_b64_tr_b16 v[240:241], v187 offset:0x3c00
	s_waitcnt lgkmcnt(8)
	v_mfma_f32_32x32x16_bf16 v[48:63], v[34:37], v[218:221], v[48:63]
	v_mfma_f32_32x32x16_bf16 v[48:63], v[38:41], v[230:233], v[48:63]
	v_mfma_f32_32x32x16_bf16 v[48:63], v[42:45], v[234:237], v[48:63]
	v_mfma_f32_32x32x16_bf16 v[48:63], v[160:163], v[242:245], v[48:63]
	ds_read_b64_tr_b16 v[218:219], v187 offset:0x600
	ds_read_b64_tr_b16 v[220:221], v187 offset:0xe00
	ds_read_b64_tr_b16 v[230:231], v187 offset:0x1600
	ds_read_b64_tr_b16 v[232:233], v187 offset:0x1e00
	ds_read_b64_tr_b16 v[234:235], v187 offset:0x2600
	ds_read_b64_tr_b16 v[236:237], v187 offset:0x2e00
	ds_read_b64_tr_b16 v[242:243], v187 offset:0x3600
	ds_read_b64_tr_b16 v[244:245], v187 offset:0x3e00
	s_waitcnt lgkmcnt(8)
	v_mfma_f32_32x32x16_bf16 v[16:31], v[34:37], v[214:217], v[16:31]
	v_mfma_f32_32x32x16_bf16 v[16:31], v[38:41], v[222:225], v[16:31]
	v_mfma_f32_32x32x16_bf16 v[16:31], v[42:45], v[226:229], v[16:31]
	v_mfma_f32_32x32x16_bf16 v[16:31], v[160:163], v[238:241], v[16:31]
	s_waitcnt lgkmcnt(0)
	v_mfma_f32_32x32x16_bf16 v[0:15], v[34:37], v[218:221], v[0:15]
	v_mfma_f32_32x32x16_bf16 v[0:15], v[38:41], v[230:233], v[0:15]
	v_mfma_f32_32x32x16_bf16 v[0:15], v[42:45], v[234:237], v[0:15]
	v_mfma_f32_32x32x16_bf16 v[0:15], v[160:163], v[242:245], v[0:15]
	s_setprio 0
	s_and_b64 vcc, exec, s[6:7]
	s_cbranch_vccnz .LBB0_1135
	s_mul_i32 s30, s70, s63
	s_add_i32 s30, s30, s46
	s_bfe_u32 s34, s30, 0x40003
	s_lshl_b32 s31, s30, 4
	s_lshl_b32 s30, s30, 8
	s_and_b32 s31, s31, 0xfffff800
	s_and_b32 s30, s30, 0x700
	s_or_b32 s30, s31, s30
	v_add_u32_e32 v36, s30, v212
	v_mov_b64_e32 v[34:35], s[16:17]
	v_mad_i64_i32 v[34:35], s[30:31], v36, s49, v[34:35]
	s_mul_i32 s40, s34, 0x180
	v_lshl_add_u64 v[34:35], v[34:35], 0, s[40:41]
	v_mov_b32_e32 v187, v32
	v_lshl_add_u64 v[34:35], v[34:35], 0, v[186:187]
	global_load_dwordx4 v[112:115], v[34:35], off
	global_load_dwordx4 v[116:119], v[34:35], off offset:32
	global_load_dwordx4 v[120:123], v[34:35], off offset:64
	global_load_dwordx4 v[124:127], v[34:35], off offset:96
	global_load_dwordx4 v[128:131], v[34:35], off offset:128
	global_load_dwordx4 v[132:135], v[34:35], off offset:160
	global_load_dwordx4 v[136:139], v[34:35], off offset:192
	global_load_dwordx4 v[140:143], v[34:35], off offset:224
	global_load_dwordx4 v[144:147], v[34:35], off offset:256
	global_load_dwordx4 v[148:151], v[34:35], off offset:288
	global_load_dwordx4 v[152:155], v[34:35], off offset:320
	global_load_dwordx4 v[156:159], v[34:35], off offset:352
